# one static s_setprio 1 for waves 0-3 for the whole attention phase (prompt and sample units), reset at phase exit
# baseline (speedup 1.0000x reference)
; #define LAS __attribute__((address_space(3)))
; __device__ __forceinline__ void fox_attention(const Args& a, LAS unsigned char* lds, int vcu, int G) {
; #pragma unroll 1
;     for (int pass = 0; pass < 2; ++pass) {
;         if ((pass ^ (vcu & 1)) == 0) {
;     ...
;           for (int rep2_ = 0; rep2_ < 2; ++rep2_)
;     ...
;             if (G == 256) {
;                 const int bh = vcu >> 1, s0 = 2 * (vcu & 1);
; #pragma unroll 1
;                 for (int i = 0; i < 4; ++i) attn_unit_prompt(a, lds, bh >> 4, bh & 15, (i & 1) ? s0 + (i >> 1) : 7 - s0 - (i >> 1));
.LBB0_1632:
	s_cmp_lt_i32 s30, 11
	s_cselect_b64 s[4:5], -1, 0
	s_and_b64 s[0:1], s[4:5], s[0:1]
	s_andn2_b64 vcc, exec, s[0:1]
	s_cbranch_vccnz .LBB0_1758
	s_and_b32 s3, s96, 1
	s_cmpk_lt_i32 s96, 0x200
	s_cselect_b64 s[6:7], -1, 0
	s_cmpk_lg_i32 s34, 0x100
	s_cselect_b64 s[8:9], -1, 0
	s_cmpk_lt_i32 s96, 0x400
	s_cselect_b64 s[10:11], -1, 0
	s_ashr_i32 s0, s96, 5
	s_bfe_u32 s14, s96, 0x40001
	s_lshl_b32 s61, s0, 11
	s_lshl_b32 s0, s0, 4
	s_or_b32 s0, s0, s14
	s_lshl_b32 s35, s3, 1
	s_ashr_i32 s1, s0, 31
	s_xor_b32 s60, s35, 7
	s_lshl_b64 s[0:1], s[0:1], 13
	s_lshl_b32 s62, s14, 6
	s_add_u32 s63, s28, 0x25900000
	s_addc_u32 s78, s29, 0
	s_add_u32 s79, s28, 0x25800000
	s_addc_u32 s80, s29, 0
	s_lshl_b32 s14, s14, 7
	s_add_u32 s22, s26, s14
	s_addc_u32 s23, s27, 0
	s_add_u32 s24, s36, s14
	s_addc_u32 s25, s37, 0
	s_add_u32 s38, s79, s0
	v_mbcnt_lo_u32_b32 v2, -1, 0
	s_mov_b32 s15, 0
	s_addc_u32 s39, s80, s1
	s_mov_b64 s[40:41], -1
	s_movk_i32 s81, 0x1800
	s_waitcnt vmcnt(0)
	v_mov_b32_e32 v67, 0
	s_movk_i32 s82, 0x2000
	s_movk_i32 s83, 0x90
	s_movk_i32 s84, 0x1000
	s_mov_b64 s[42:43], 0x1000
	s_mov_b64 s[44:45], 0x1f00
	s_mov_b64 s[46:47], 0x1e00
	s_mov_b64 s[48:49], 0x1d00
	s_movk_i32 s85, 0x220
	s_mov_b32 s86, 0xffff0000
	s_movk_i32 s87, 0xc0
	s_mov_b32 s88, 0xbfb8aa3b
	s_movk_i32 s89, 0x7fff
	s_mov_b64 s[50:51], 0x1c00
	s_mov_b64 s[52:53], 0x800
	s_mov_b64 s[54:55], 0x2800
	s_mov_b64 s[66:67], 0x200
	s_mov_b64 s[68:69], 0x100
	s_movk_i32 s90, 0x48
	v_mov_b32_e32 v148, 0x1200
	v_mov_b32_e32 v149, 0xff800000
	v_mbcnt_hi_u32_b32 v150, -1, v2
	s_mov_b32 s0, 0
	v_readfirstlane_b32 s98, v0
	s_nop 3
	s_lshr_b32 s98, s98, 6
	s_cmp_ge_u32 s98, 4
	s_cbranch_scc1 .Lp10_prio_done
	s_setprio 1
.Lp10_prio_done:
	s_branch .LBB0_1635
.LBB0_1634:
	s_xor_b64 s[40:41], s[40:41], -1
	s_mov_b32 s0, 1
	s_andn2_b64 vcc, exec, s[40:41]
	s_mov_b64 s[40:41], 0
	s_cbranch_vccz .LBB0_1758
